# idle workgroups of the gate/up last round (blockIdx>=128, layers 0-1) draw up to 2 chunks/wave from the next layer's weight-conversion queue
# baseline (speedup 1.0000x reference)
; __device__ __forceinline__ unsigned xb_xcc_id() { return (unsigned)__builtin_amdgcn_s_getreg((3 << 11) | 20) & 0xFu; }
; #define ARG_WS() ((unsigned char*)karg64(8 * 19))
; #define WV_DRAW(cls, q, n) int it = 0; if (__builtin_amdgcn_mbcnt_hi(~0u, __builtin_amdgcn_mbcnt_lo(~0u, 0u)) == 0u) it = (int)__hip_atomic_fetch_add(XQ_HEAD(cls, q), (unsigned)(n), RLX_AGENT); it = __builtin_amdgcn_readfirstlane(it);
; template <int ATTM> __device__ __forceinline__ void attention_phase(int layer, int lane, int rep, LAS unsigned char* lds, int wave) {
;     ...
;     if (!(ATTM & 32) && PK(16) && layer + 1 < DEPTH) {
; #pragma unroll 1
;         for (int qq = 0; qq < 8; ++qq) { const int q = ((int)(xb_xcc_id() & 7u) + qq) & 7;
;             for (;;) { WV_DRAW(4, q, 4); if (it >= I_LAYER / 8) break; unsigned char* ws = ARG_WS();
.LBB0_876:
	s_mov_b32 s99, 0
	s_mov_b32 s98, 0x7fffffff

; __device__ __forceinline__ int fresh_lane() { int l = (int)__builtin_amdgcn_mbcnt_hi(~0u, __builtin_amdgcn_mbcnt_lo(~0u, 0u)); asm volatile("" : "+v"(l)); return l; }
; #define ARG_IN(i) ((const float*)karg64(8 * (i)))
; #define ARG_WS() ((unsigned char*)karg64(8 * 19))
; #define WV_DRAW(cls, q, n) int it = 0; if (__builtin_amdgcn_mbcnt_hi(~0u, __builtin_amdgcn_mbcnt_lo(~0u, 0u)) == 0u) it = (int)__hip_atomic_fetch_add(XQ_HEAD(cls, q), (unsigned)(n), RLX_AGENT); it = __builtin_amdgcn_readfirstlane(it);
; template <int ATTM> __device__ __forceinline__ void attention_phase(int layer, int lane, int rep, LAS unsigned char* lds, int wave) {
;     ...
;             for (;;) { WV_DRAW(4, q, 4); if (it >= I_LAYER / 8) break; unsigned char* ws = ARG_WS();
; #pragma unroll 1
;                 for (int k = it; k < it + 4 && k < I_LAYER / 8; ++k) conv_item(ARG_IN(A_WIN), ARG_IN(A_WOUT), ARG_IN(A_WGATE), ARG_IN(A_WUP), ARG_IN(A_WDOWN), ws, layer + 1, q * (I_LAYER / 8) + k, lds + wave * 16384, fresh_lane()); } } }
.LBB0_882:
	s_sub_u32 s98, s98, 1
	s_cmp_eq_u32 s98, 0
	s_cbranch_scc1 .Lmy_ec_ret
	v_mov_b32_e32 v1, 0
	s_and_saveexec_b64 s[2:3], s[38:39]
	s_cbranch_execz .LBB0_886
	s_waitcnt lgkmcnt(0)
	s_load_dwordx2 s[20:21], s[0:1], 0x98
	s_mov_b64 s[16:17], exec
	v_mbcnt_lo_u32_b32 v1, s16, 0
	v_mbcnt_hi_u32_b32 v1, s17, v1
	v_cmp_eq_u32_e32 vcc, 0, v1
	s_and_saveexec_b64 s[14:15], vcc
	s_cbranch_execz .LBB0_885
	s_waitcnt lgkmcnt(0)
	s_add_u32 s6, s20, s44
	s_addc_u32 s7, s21, s45
	s_bcnt1_i32_b64 s4, s[16:17]
	s_lshl_b32 s4, s4, 2
	v_mov_b32_e32 v2, s4
	global_atomic_add v2, v231, v2, s[6:7] sc0

; __device__ __forceinline__ unsigned xb_xcc_id() { return (unsigned)__builtin_amdgcn_s_getreg((3 << 11) | 20) & 0xFu; }
; __device__ __forceinline__ int fresh_lane() { int l = (int)__builtin_amdgcn_mbcnt_hi(~0u, __builtin_amdgcn_mbcnt_lo(~0u, 0u)); asm volatile("" : "+v"(l)); return l; }
; #define ARG_IN(i) ((const float*)karg64(8 * (i)))
; #define ARG_WS() ((unsigned char*)karg64(8 * 19))
; #define WV_DRAW(cls, q, n) int it = 0; if (__builtin_amdgcn_mbcnt_hi(~0u, __builtin_amdgcn_mbcnt_lo(~0u, 0u)) == 0u) it = (int)__hip_atomic_fetch_add(XQ_HEAD(cls, q), (unsigned)(n), RLX_AGENT); it = __builtin_amdgcn_readfirstlane(it);
; template <int ATTM> __device__ __forceinline__ void attention_phase(int layer, int lane, int rep, LAS unsigned char* lds, int wave) {
;     ...
;     if (!(ATTM & 32) && PK(16) && layer + 1 < DEPTH) {
; #pragma unroll 1
;         for (int qq = 0; qq < 8; ++qq) { const int q = ((int)(xb_xcc_id() & 7u) + qq) & 7;
;             for (;;) { WV_DRAW(4, q, 4); if (it >= I_LAYER / 8) break; unsigned char* ws = ARG_WS();
; #pragma unroll 1
;                 for (int k = it; k < it + 4 && k < I_LAYER / 8; ++k) conv_item(ARG_IN(A_WIN), ARG_IN(A_WOUT), ARG_IN(A_WGATE), ARG_IN(A_WUP), ARG_IN(A_WDOWN), ws, layer + 1, q * (I_LAYER / 8) + k, lds + wave * 16384, fresh_lane()); } } }
;     if (!(ATTM & 32) && PK(16) && layer == 0) {
.LBB0_1428:
	s_cmp_lg_u32 s99, 0
	s_cbranch_scc1 .Lmy_ec_ret
	v_readlane_b32 s2, v255, 21
	s_cmp_lg_u32 s2, 0
	v_readlane_b32 s3, v255, 22
	s_cbranch_scc0 .LBB0_1442

; __device__ __forceinline__ unsigned xb_add(unsigned* p, unsigned v) { return __hip_atomic_fetch_add(p, v, __ATOMIC_RELAXED, __HIP_MEMORY_SCOPE_AGENT); }
; #define ARG_WS() ((unsigned char*)karg64(8 * 19))
; #define REP(k) for (int rep_ = 0; rep_ < (DUP_PHASE == (k) ? 2 : 1); ++rep_, (DUP_PHASE == (k) ? xcd_barrier(bar) : (void)0))
; #define IDX() int tid = threadIdx.x, bid = blockIdx.x, G = gridDim.x; asm volatile("" : "+v"(tid)); asm volatile("" : "+s"(bid), "+s"(G)); \
;     const int lane = tid & 63, wave = __builtin_amdgcn_readfirstlane(tid >> 6), gw = bid * NWAVES + wave, NGW = G * NWAVES; (void)lane; (void)gw; (void)NGW; (void)wave
; #define SEAM(k) do { if (N_LAUNCH_MODE == 0 && IN(k) && IN((k) + 1)) xcd_barrier(bar); } while (0)
; __device__ __forceinline__ void xcd_barrier(const XcdBarrier& b) {
;     asm volatile("s_waitcnt vmcnt(0)" ::: "memory");
;     __syncthreads();
;     if (threadIdx.x == 0) {
;         unsigned* bar = b.bar;
;         __builtin_amdgcn_s_waitcnt(0);
;         unsigned nloc = b.st[0], nx = b.st[1];
;         if (nloc == 0u) { xcd_barrier_complete(bar, b.x, nloc, nx); b.st[0] = nloc; b.st[1] = nx; }
;         const unsigned old = xb_add(&bar[XB_XSUB(b.x)], 1u);
;         const unsigned gen = old / nloc;
;         if (old + 1u == (gen + 1u) * nloc) {
; template <int PHM, int ATTM> __global__ void __launch_bounds__(NWAVES * 64, 2) fwd_kernel(Args args) {
;     ...
;         REP(8) if (IN(pb + 7) && EN(8)) { IDX(); unsigned char* ws = ARG_WS();
;             pg8::Gemm g{WSP(bf16, WS_U), WSP(bf16, WS_W + (size_t)layer * W_LAYER + W_GU), M, NGU, DM}; pg8::StaticOrder S; S.init(M, NGU, G, bid);
;             pg8::EpiSwiglu E{WSP(bf16, WS_ACT), DFF}; pg8::gemm_phase<pg8::EpiSwiglu, pg8::StaticOrder, true, true>(lds, g, S, E); }
;         SEAM(pb + 7);
.LBB0_2171:
	s_waitcnt vmcnt(0)
	s_barrier
	v_readlane_b32 s4, v255, 21
	s_cmp_gt_u32 s4, 1
	s_cbranch_scc1 .Lmy_ec_skip
	s_cmp_lt_u32 s66, 0x80
	s_cbranch_scc1 .Lmy_ec_skip
	v_writelane_b32 v255, s2, 32
	v_writelane_b32 v255, s3, 33
	s_add_i32 s4, s4, 1
	v_writelane_b32 v255, s4, 21
	s_mul_i32 s64, s4, 40
	v_readfirstlane_b32 s5, v0
	s_lshr_b32 s5, s5, 6
	s_lshl_b32 s46, s5, 14
	v_cmp_eq_u32_e64 s[38:39], 0, v239
	s_mov_b32 s99, 1
	s_mov_b32 s98, 3
	s_nop 3
	s_branch .Lmy_ec_entry
.Lmy_ec_ret:
	v_readlane_b32 s4, v255, 21
	s_mov_b32 s99, 0
	s_sub_i32 s4, s4, 1
	v_writelane_b32 v255, s4, 21
	v_readlane_b32 s2, v255, 32
	v_readlane_b32 s3, v255, 33
	s_nop 3
.Lmy_ec_skip:
.LBB0_2172:
	v_readlane_b32 s4, v255, 20
	s_add_i32 s4, s4, 9
	s_cmp_lt_i32 s4, s67
	s_cselect_b64 s[14:15], -1, 0
	s_and_b64 s[2:3], s[2:3], s[14:15]
	s_andn2_b64 vcc, exec, s[2:3]
	s_cbranch_vccnz .LBB0_2218
	s_waitcnt vmcnt(0)
	s_waitcnt vmcnt(0) lgkmcnt(0)
	s_barrier
	s_and_saveexec_b64 s[2:3], s[70:71]
	s_cbranch_execz .LBB0_2217
	v_readlane_b32 s5, v255, 11
	s_waitcnt vmcnt(0) expcnt(0) lgkmcnt(0)
	s_nop 0
	v_mov_b32_e32 v1, s5
	ds_read_b32 v4, v1
	v_readlane_b32 s5, v255, 12
	s_waitcnt lgkmcnt(0)
	v_cmp_ne_u32_e32 vcc, 0, v4
	v_mov_b32_e32 v1, s5
	ds_read_b32 v2, v1
	s_cbranch_vccnz .LBB0_2188
	s_load_dwordx2 s[6:7], s[72:73], 0x0
	s_load_dword s8, s[72:73], 0x8
	s_mov_b32 s5, 1
	s_mov_b64 s[16:17], 0
	s_waitcnt lgkmcnt(0)
	s_mul_i32 s6, s7, s6
	s_mul_i32 s6, s6, s8
	s_branch .LBB0_2178
